# SwiGLU GEMM epilogue rewritten: packed f32 mul/add, no hazard nops, LDS param reads issued together, plain rsq (bit-identical math)
# speedup vs baseline: 1.0106x; 1.0068x over previous
.LBB0_259:
	v_mov_b32_e32 v74, s88
	v_mov_b32_e32 v75, s89
	ds_read_b32 v74, v74
	ds_read_b32 v75, v75
	ds_read2_b32 v[76:77], v173 offset1:16
	ds_read2_b32 v[78:79], v173 offset0:32 offset1:48
	ds_read2_b32 v[80:81], v173 offset0:64 offset1:80
	ds_read2_b32 v[90:91], v173 offset0:96 offset1:112
	ds_read_b128 v[188:191], v179 offset:512
	ds_read_b128 v[192:195], v179 offset:528
	ds_read_b128 v[196:199], v179 offset:544
	ds_read_b128 v[200:203], v179 offset:560
	v_lshl_or_b32 v186, s3, 7, v175
	v_ashrrev_i32_e32 v187, 31, v186
	v_lshl_add_u32 v155, s46, 8, v1
	v_mov_b32_e32 v204, 0xbfb8aa3b
	v_mov_b32_e32 v205, 1.0
	s_waitcnt lgkmcnt(8)
	v_lshl_add_u64 v[168:169], v[186:187], 1, v[74:75]
	v_lshl_add_u64 v[168:169], v[168:169], 0, s[78:79]
	v_mad_i64_i32 v[214:215], s[20:21], v155, s71, v[168:169]
	s_waitcnt lgkmcnt(4)
	v_fmamk_f32 v184, v76, 0x3a800000, v229
	v_fmamk_f32 v182, v77, 0x3a800000, v229
	v_fmamk_f32 v180, v78, 0x3a800000, v229
	v_fmamk_f32 v178, v79, 0x3a800000, v229
	v_fmamk_f32 v176, v80, 0x3a800000, v229
	v_fmamk_f32 v174, v81, 0x3a800000, v229
	v_fmamk_f32 v172, v90, 0x3a800000, v229
	v_fmamk_f32 v170, v91, 0x3a800000, v229
	v_rsq_f32_e32 v184, v184
	v_rsq_f32_e32 v182, v182
	v_rsq_f32_e32 v180, v180
	v_rsq_f32_e32 v178, v178
	v_rsq_f32_e32 v176, v176
	v_rsq_f32_e32 v174, v174
	v_rsq_f32_e32 v172, v172
	v_rsq_f32_e32 v170, v170
	s_mov_b32 s20, 0x16000
	s_mov_b32 s21, 0
	s_waitcnt lgkmcnt(0)
	v_pk_fma_f32 v[142:143], v[142:143], v[184:185], v[188:189] op_sel_hi:[1,0,1]
	v_pk_fma_f32 v[144:145], v[144:145], v[184:185], v[190:191] op_sel_hi:[1,0,1]
	v_pk_fma_f32 v[134:135], v[134:135], v[184:185], v[192:193] op_sel_hi:[1,0,1]
	v_pk_fma_f32 v[136:137], v[136:137], v[184:185], v[194:195] op_sel_hi:[1,0,1]
	v_pk_mul_f32 v[206:207], v[142:143], v[204:205] op_sel_hi:[1,0]
	v_pk_mul_f32 v[208:209], v[144:145], v[204:205] op_sel_hi:[1,0]
	v_pk_mul_f32 v[210:211], v[134:135], v[204:205] op_sel_hi:[1,0]
	v_pk_mul_f32 v[212:213], v[136:137], v[204:205] op_sel_hi:[1,0]
	v_pk_fma_f32 v[138:139], v[138:139], v[184:185], v[196:197] op_sel_hi:[1,0,1]
	v_pk_fma_f32 v[140:141], v[140:141], v[184:185], v[198:199] op_sel_hi:[1,0,1]
	v_pk_fma_f32 v[130:131], v[130:131], v[184:185], v[200:201] op_sel_hi:[1,0,1]
	v_pk_fma_f32 v[132:133], v[132:133], v[184:185], v[202:203] op_sel_hi:[1,0,1]
	v_exp_f32_e32 v206, v206
	v_exp_f32_e32 v207, v207
	v_exp_f32_e32 v208, v208
	v_exp_f32_e32 v209, v209
	v_exp_f32_e32 v210, v210
	v_exp_f32_e32 v211, v211
	v_exp_f32_e32 v212, v212
	v_exp_f32_e32 v213, v213
	v_pk_add_f32 v[206:207], v[206:207], v[204:205] op_sel:[0,1] op_sel_hi:[1,1]
	v_pk_add_f32 v[208:209], v[208:209], v[204:205] op_sel:[0,1] op_sel_hi:[1,1]
	v_pk_add_f32 v[210:211], v[210:211], v[204:205] op_sel:[0,1] op_sel_hi:[1,1]
	v_pk_add_f32 v[212:213], v[212:213], v[204:205] op_sel:[0,1] op_sel_hi:[1,1]
	v_rcp_f32_e32 v206, v206
	v_rcp_f32_e32 v207, v207
	v_rcp_f32_e32 v208, v208
	v_rcp_f32_e32 v209, v209
	v_rcp_f32_e32 v210, v210
	v_rcp_f32_e32 v211, v211
	v_rcp_f32_e32 v212, v212
	v_rcp_f32_e32 v213, v213
	v_pk_mul_f32 v[142:143], v[142:143], v[206:207]
	v_pk_mul_f32 v[144:145], v[144:145], v[208:209]
	v_pk_mul_f32 v[134:135], v[134:135], v[210:211]
	v_pk_mul_f32 v[136:137], v[136:137], v[212:213]
	v_pk_mul_f32 v[138:139], v[138:139], v[142:143]
	v_pk_mul_f32 v[140:141], v[140:141], v[144:145]
	v_pk_mul_f32 v[130:131], v[130:131], v[134:135]
	v_pk_mul_f32 v[132:133], v[132:133], v[136:137]
	v_cvt_pk_bf16_f32 v142, v138, v139
	v_cvt_pk_bf16_f32 v143, v140, v141
	v_cvt_pk_bf16_f32 v144, v130, v131
	v_cvt_pk_bf16_f32 v145, v132, v133
	global_store_dwordx4 v[214:215], v[142:145], off
	v_lshl_add_u64 v[216:217], v[214:215], 0, s[20:21]
	v_pk_fma_f32 v[126:127], v[126:127], v[182:183], v[188:189] op_sel_hi:[1,0,1]
	v_pk_fma_f32 v[128:129], v[128:129], v[182:183], v[190:191] op_sel_hi:[1,0,1]
	v_pk_fma_f32 v[118:119], v[118:119], v[182:183], v[192:193] op_sel_hi:[1,0,1]
	v_pk_fma_f32 v[120:121], v[120:121], v[182:183], v[194:195] op_sel_hi:[1,0,1]
	v_pk_mul_f32 v[206:207], v[126:127], v[204:205] op_sel_hi:[1,0]
	v_pk_mul_f32 v[208:209], v[128:129], v[204:205] op_sel_hi:[1,0]
	v_pk_mul_f32 v[210:211], v[118:119], v[204:205] op_sel_hi:[1,0]
	v_pk_mul_f32 v[212:213], v[120:121], v[204:205] op_sel_hi:[1,0]
	v_pk_fma_f32 v[122:123], v[122:123], v[182:183], v[196:197] op_sel_hi:[1,0,1]
	v_pk_fma_f32 v[124:125], v[124:125], v[182:183], v[198:199] op_sel_hi:[1,0,1]
	v_pk_fma_f32 v[114:115], v[114:115], v[182:183], v[200:201] op_sel_hi:[1,0,1]
	v_pk_fma_f32 v[116:117], v[116:117], v[182:183], v[202:203] op_sel_hi:[1,0,1]
	v_exp_f32_e32 v206, v206
	v_exp_f32_e32 v207, v207
	v_exp_f32_e32 v208, v208
	v_exp_f32_e32 v209, v209
	v_exp_f32_e32 v210, v210
	v_exp_f32_e32 v211, v211
	v_exp_f32_e32 v212, v212
	v_exp_f32_e32 v213, v213
	v_pk_add_f32 v[206:207], v[206:207], v[204:205] op_sel:[0,1] op_sel_hi:[1,1]
	v_pk_add_f32 v[208:209], v[208:209], v[204:205] op_sel:[0,1] op_sel_hi:[1,1]
	v_pk_add_f32 v[210:211], v[210:211], v[204:205] op_sel:[0,1] op_sel_hi:[1,1]
	v_pk_add_f32 v[212:213], v[212:213], v[204:205] op_sel:[0,1] op_sel_hi:[1,1]
	v_rcp_f32_e32 v206, v206
	v_rcp_f32_e32 v207, v207
	v_rcp_f32_e32 v208, v208
	v_rcp_f32_e32 v209, v209
	v_rcp_f32_e32 v210, v210
	v_rcp_f32_e32 v211, v211
	v_rcp_f32_e32 v212, v212
	v_rcp_f32_e32 v213, v213
	v_pk_mul_f32 v[126:127], v[126:127], v[206:207]
	v_pk_mul_f32 v[128:129], v[128:129], v[208:209]
	v_pk_mul_f32 v[118:119], v[118:119], v[210:211]
	v_pk_mul_f32 v[120:121], v[120:121], v[212:213]
	v_pk_mul_f32 v[122:123], v[122:123], v[126:127]
	v_pk_mul_f32 v[124:125], v[124:125], v[128:129]
	v_pk_mul_f32 v[114:115], v[114:115], v[118:119]
	v_pk_mul_f32 v[116:117], v[116:117], v[120:121]
	v_cvt_pk_bf16_f32 v126, v122, v123
	v_cvt_pk_bf16_f32 v127, v124, v125
	v_cvt_pk_bf16_f32 v128, v114, v115
	v_cvt_pk_bf16_f32 v129, v116, v117
	global_store_dwordx4 v[216:217], v[126:129], off
	v_lshl_add_u64 v[214:215], v[216:217], 0, s[20:21]
	v_pk_fma_f32 v[110:111], v[110:111], v[180:181], v[188:189] op_sel_hi:[1,0,1]
	v_pk_fma_f32 v[112:113], v[112:113], v[180:181], v[190:191] op_sel_hi:[1,0,1]
	v_pk_fma_f32 v[102:103], v[102:103], v[180:181], v[192:193] op_sel_hi:[1,0,1]
	v_pk_fma_f32 v[104:105], v[104:105], v[180:181], v[194:195] op_sel_hi:[1,0,1]
	v_pk_mul_f32 v[206:207], v[110:111], v[204:205] op_sel_hi:[1,0]
	v_pk_mul_f32 v[208:209], v[112:113], v[204:205] op_sel_hi:[1,0]
	v_pk_mul_f32 v[210:211], v[102:103], v[204:205] op_sel_hi:[1,0]
	v_pk_mul_f32 v[212:213], v[104:105], v[204:205] op_sel_hi:[1,0]
	v_pk_fma_f32 v[106:107], v[106:107], v[180:181], v[196:197] op_sel_hi:[1,0,1]
	v_pk_fma_f32 v[108:109], v[108:109], v[180:181], v[198:199] op_sel_hi:[1,0,1]
	v_pk_fma_f32 v[98:99], v[98:99], v[180:181], v[200:201] op_sel_hi:[1,0,1]
	v_pk_fma_f32 v[100:101], v[100:101], v[180:181], v[202:203] op_sel_hi:[1,0,1]
	v_exp_f32_e32 v206, v206
	v_exp_f32_e32 v207, v207
	v_exp_f32_e32 v208, v208
	v_exp_f32_e32 v209, v209
	v_exp_f32_e32 v210, v210
	v_exp_f32_e32 v211, v211
	v_exp_f32_e32 v212, v212
	v_exp_f32_e32 v213, v213
	v_pk_add_f32 v[206:207], v[206:207], v[204:205] op_sel:[0,1] op_sel_hi:[1,1]
	v_pk_add_f32 v[208:209], v[208:209], v[204:205] op_sel:[0,1] op_sel_hi:[1,1]
	v_pk_add_f32 v[210:211], v[210:211], v[204:205] op_sel:[0,1] op_sel_hi:[1,1]
	v_pk_add_f32 v[212:213], v[212:213], v[204:205] op_sel:[0,1] op_sel_hi:[1,1]
	v_rcp_f32_e32 v206, v206
	v_rcp_f32_e32 v207, v207
	v_rcp_f32_e32 v208, v208
	v_rcp_f32_e32 v209, v209
	v_rcp_f32_e32 v210, v210
	v_rcp_f32_e32 v211, v211
	v_rcp_f32_e32 v212, v212
	v_rcp_f32_e32 v213, v213
	v_pk_mul_f32 v[110:111], v[110:111], v[206:207]
	v_pk_mul_f32 v[112:113], v[112:113], v[208:209]
	v_pk_mul_f32 v[102:103], v[102:103], v[210:211]
	v_pk_mul_f32 v[104:105], v[104:105], v[212:213]
	v_pk_mul_f32 v[106:107], v[106:107], v[110:111]
	v_pk_mul_f32 v[108:109], v[108:109], v[112:113]
	v_pk_mul_f32 v[98:99], v[98:99], v[102:103]
	v_pk_mul_f32 v[100:101], v[100:101], v[104:105]
	v_cvt_pk_bf16_f32 v110, v106, v107
	v_cvt_pk_bf16_f32 v111, v108, v109
	v_cvt_pk_bf16_f32 v112, v98, v99
	v_cvt_pk_bf16_f32 v113, v100, v101
	global_store_dwordx4 v[214:215], v[110:113], off
	v_lshl_add_u64 v[216:217], v[214:215], 0, s[20:21]
	v_pk_fma_f32 v[86:87], v[86:87], v[178:179], v[188:189] op_sel_hi:[1,0,1]
	v_pk_fma_f32 v[88:89], v[88:89], v[178:179], v[190:191] op_sel_hi:[1,0,1]
	v_pk_fma_f32 v[70:71], v[70:71], v[178:179], v[192:193] op_sel_hi:[1,0,1]
	v_pk_fma_f32 v[72:73], v[72:73], v[178:179], v[194:195] op_sel_hi:[1,0,1]
	v_pk_mul_f32 v[206:207], v[86:87], v[204:205] op_sel_hi:[1,0]
	v_pk_mul_f32 v[208:209], v[88:89], v[204:205] op_sel_hi:[1,0]
	v_pk_mul_f32 v[210:211], v[70:71], v[204:205] op_sel_hi:[1,0]
	v_pk_mul_f32 v[212:213], v[72:73], v[204:205] op_sel_hi:[1,0]
	v_pk_fma_f32 v[82:83], v[82:83], v[178:179], v[196:197] op_sel_hi:[1,0,1]
	v_pk_fma_f32 v[84:85], v[84:85], v[178:179], v[198:199] op_sel_hi:[1,0,1]
	v_pk_fma_f32 v[66:67], v[66:67], v[178:179], v[200:201] op_sel_hi:[1,0,1]
	v_pk_fma_f32 v[68:69], v[68:69], v[178:179], v[202:203] op_sel_hi:[1,0,1]
	v_exp_f32_e32 v206, v206
	v_exp_f32_e32 v207, v207
	v_exp_f32_e32 v208, v208
	v_exp_f32_e32 v209, v209
	v_exp_f32_e32 v210, v210
	v_exp_f32_e32 v211, v211
	v_exp_f32_e32 v212, v212
	v_exp_f32_e32 v213, v213
	v_pk_add_f32 v[206:207], v[206:207], v[204:205] op_sel:[0,1] op_sel_hi:[1,1]
	v_pk_add_f32 v[208:209], v[208:209], v[204:205] op_sel:[0,1] op_sel_hi:[1,1]
	v_pk_add_f32 v[210:211], v[210:211], v[204:205] op_sel:[0,1] op_sel_hi:[1,1]
	v_pk_add_f32 v[212:213], v[212:213], v[204:205] op_sel:[0,1] op_sel_hi:[1,1]
	v_rcp_f32_e32 v206, v206
	v_rcp_f32_e32 v207, v207
	v_rcp_f32_e32 v208, v208
	v_rcp_f32_e32 v209, v209
	v_rcp_f32_e32 v210, v210
	v_rcp_f32_e32 v211, v211
	v_rcp_f32_e32 v212, v212
	v_rcp_f32_e32 v213, v213
	v_pk_mul_f32 v[86:87], v[86:87], v[206:207]
	v_pk_mul_f32 v[88:89], v[88:89], v[208:209]
	v_pk_mul_f32 v[70:71], v[70:71], v[210:211]
	v_pk_mul_f32 v[72:73], v[72:73], v[212:213]
	v_pk_mul_f32 v[82:83], v[82:83], v[86:87]
	v_pk_mul_f32 v[84:85], v[84:85], v[88:89]
	v_pk_mul_f32 v[66:67], v[66:67], v[70:71]
	v_pk_mul_f32 v[68:69], v[68:69], v[72:73]
	v_cvt_pk_bf16_f32 v86, v82, v83
	v_cvt_pk_bf16_f32 v87, v84, v85
	v_cvt_pk_bf16_f32 v88, v66, v67
	v_cvt_pk_bf16_f32 v89, v68, v69
	global_store_dwordx4 v[216:217], v[86:89], off
	s_mov_b32 s20, 0x6e000
	v_lshl_add_u64 v[214:215], v[216:217], 0, s[20:21]
	s_mov_b32 s20, 0x16000
	v_pk_fma_f32 v[62:63], v[62:63], v[176:177], v[188:189] op_sel_hi:[1,0,1]
	v_pk_fma_f32 v[64:65], v[64:65], v[176:177], v[190:191] op_sel_hi:[1,0,1]
	v_pk_fma_f32 v[54:55], v[54:55], v[176:177], v[192:193] op_sel_hi:[1,0,1]
	v_pk_fma_f32 v[56:57], v[56:57], v[176:177], v[194:195] op_sel_hi:[1,0,1]
	v_pk_mul_f32 v[206:207], v[62:63], v[204:205] op_sel_hi:[1,0]
	v_pk_mul_f32 v[208:209], v[64:65], v[204:205] op_sel_hi:[1,0]
	v_pk_mul_f32 v[210:211], v[54:55], v[204:205] op_sel_hi:[1,0]
	v_pk_mul_f32 v[212:213], v[56:57], v[204:205] op_sel_hi:[1,0]
	v_pk_fma_f32 v[58:59], v[58:59], v[176:177], v[196:197] op_sel_hi:[1,0,1]
	v_pk_fma_f32 v[60:61], v[60:61], v[176:177], v[198:199] op_sel_hi:[1,0,1]
	v_pk_fma_f32 v[50:51], v[50:51], v[176:177], v[200:201] op_sel_hi:[1,0,1]
	v_pk_fma_f32 v[52:53], v[52:53], v[176:177], v[202:203] op_sel_hi:[1,0,1]
	v_exp_f32_e32 v206, v206
	v_exp_f32_e32 v207, v207
	v_exp_f32_e32 v208, v208
	v_exp_f32_e32 v209, v209
	v_exp_f32_e32 v210, v210
	v_exp_f32_e32 v211, v211
	v_exp_f32_e32 v212, v212
	v_exp_f32_e32 v213, v213
	v_pk_add_f32 v[206:207], v[206:207], v[204:205] op_sel:[0,1] op_sel_hi:[1,1]
	v_pk_add_f32 v[208:209], v[208:209], v[204:205] op_sel:[0,1] op_sel_hi:[1,1]
	v_pk_add_f32 v[210:211], v[210:211], v[204:205] op_sel:[0,1] op_sel_hi:[1,1]
	v_pk_add_f32 v[212:213], v[212:213], v[204:205] op_sel:[0,1] op_sel_hi:[1,1]
	v_rcp_f32_e32 v206, v206
	v_rcp_f32_e32 v207, v207
	v_rcp_f32_e32 v208, v208
	v_rcp_f32_e32 v209, v209
	v_rcp_f32_e32 v210, v210
	v_rcp_f32_e32 v211, v211
	v_rcp_f32_e32 v212, v212
	v_rcp_f32_e32 v213, v213
	v_pk_mul_f32 v[62:63], v[62:63], v[206:207]
	v_pk_mul_f32 v[64:65], v[64:65], v[208:209]
	v_pk_mul_f32 v[54:55], v[54:55], v[210:211]
	v_pk_mul_f32 v[56:57], v[56:57], v[212:213]
	v_pk_mul_f32 v[58:59], v[58:59], v[62:63]
	v_pk_mul_f32 v[60:61], v[60:61], v[64:65]
	v_pk_mul_f32 v[50:51], v[50:51], v[54:55]
	v_pk_mul_f32 v[52:53], v[52:53], v[56:57]
	v_cvt_pk_bf16_f32 v62, v58, v59
	v_cvt_pk_bf16_f32 v63, v60, v61
	v_cvt_pk_bf16_f32 v64, v50, v51
	v_cvt_pk_bf16_f32 v65, v52, v53
	global_store_dwordx4 v[214:215], v[62:65], off
	v_lshl_add_u64 v[216:217], v[214:215], 0, s[20:21]
	v_pk_fma_f32 v[46:47], v[46:47], v[174:175], v[188:189] op_sel_hi:[1,0,1]
	v_pk_fma_f32 v[48:49], v[48:49], v[174:175], v[190:191] op_sel_hi:[1,0,1]
	v_pk_fma_f32 v[38:39], v[38:39], v[174:175], v[192:193] op_sel_hi:[1,0,1]
	v_pk_fma_f32 v[40:41], v[40:41], v[174:175], v[194:195] op_sel_hi:[1,0,1]
	v_pk_mul_f32 v[206:207], v[46:47], v[204:205] op_sel_hi:[1,0]
	v_pk_mul_f32 v[208:209], v[48:49], v[204:205] op_sel_hi:[1,0]
	v_pk_mul_f32 v[210:211], v[38:39], v[204:205] op_sel_hi:[1,0]
	v_pk_mul_f32 v[212:213], v[40:41], v[204:205] op_sel_hi:[1,0]
	v_pk_fma_f32 v[42:43], v[42:43], v[174:175], v[196:197] op_sel_hi:[1,0,1]
	v_pk_fma_f32 v[44:45], v[44:45], v[174:175], v[198:199] op_sel_hi:[1,0,1]
	v_pk_fma_f32 v[34:35], v[34:35], v[174:175], v[200:201] op_sel_hi:[1,0,1]
	v_pk_fma_f32 v[36:37], v[36:37], v[174:175], v[202:203] op_sel_hi:[1,0,1]
	v_exp_f32_e32 v206, v206
	v_exp_f32_e32 v207, v207
	v_exp_f32_e32 v208, v208
	v_exp_f32_e32 v209, v209
	v_exp_f32_e32 v210, v210
	v_exp_f32_e32 v211, v211
	v_exp_f32_e32 v212, v212
	v_exp_f32_e32 v213, v213
	v_pk_add_f32 v[206:207], v[206:207], v[204:205] op_sel:[0,1] op_sel_hi:[1,1]
	v_pk_add_f32 v[208:209], v[208:209], v[204:205] op_sel:[0,1] op_sel_hi:[1,1]
	v_pk_add_f32 v[210:211], v[210:211], v[204:205] op_sel:[0,1] op_sel_hi:[1,1]
	v_pk_add_f32 v[212:213], v[212:213], v[204:205] op_sel:[0,1] op_sel_hi:[1,1]
	v_rcp_f32_e32 v206, v206
	v_rcp_f32_e32 v207, v207
	v_rcp_f32_e32 v208, v208
	v_rcp_f32_e32 v209, v209
	v_rcp_f32_e32 v210, v210
	v_rcp_f32_e32 v211, v211
	v_rcp_f32_e32 v212, v212
	v_rcp_f32_e32 v213, v213
	v_pk_mul_f32 v[46:47], v[46:47], v[206:207]
	v_pk_mul_f32 v[48:49], v[48:49], v[208:209]
	v_pk_mul_f32 v[38:39], v[38:39], v[210:211]
	v_pk_mul_f32 v[40:41], v[40:41], v[212:213]
	v_pk_mul_f32 v[42:43], v[42:43], v[46:47]
	v_pk_mul_f32 v[44:45], v[44:45], v[48:49]
	v_pk_mul_f32 v[34:35], v[34:35], v[38:39]
	v_pk_mul_f32 v[36:37], v[36:37], v[40:41]
	v_cvt_pk_bf16_f32 v46, v42, v43
	v_cvt_pk_bf16_f32 v47, v44, v45
	v_cvt_pk_bf16_f32 v48, v34, v35
	v_cvt_pk_bf16_f32 v49, v36, v37
	global_store_dwordx4 v[216:217], v[46:49], off
	v_lshl_add_u64 v[214:215], v[216:217], 0, s[20:21]
	v_pk_fma_f32 v[30:31], v[30:31], v[172:173], v[188:189] op_sel_hi:[1,0,1]
	v_pk_fma_f32 v[32:33], v[32:33], v[172:173], v[190:191] op_sel_hi:[1,0,1]
	v_pk_fma_f32 v[22:23], v[22:23], v[172:173], v[192:193] op_sel_hi:[1,0,1]
	v_pk_fma_f32 v[24:25], v[24:25], v[172:173], v[194:195] op_sel_hi:[1,0,1]
	v_pk_mul_f32 v[206:207], v[30:31], v[204:205] op_sel_hi:[1,0]
	v_pk_mul_f32 v[208:209], v[32:33], v[204:205] op_sel_hi:[1,0]
	v_pk_mul_f32 v[210:211], v[22:23], v[204:205] op_sel_hi:[1,0]
	v_pk_mul_f32 v[212:213], v[24:25], v[204:205] op_sel_hi:[1,0]
	v_pk_fma_f32 v[26:27], v[26:27], v[172:173], v[196:197] op_sel_hi:[1,0,1]
	v_pk_fma_f32 v[28:29], v[28:29], v[172:173], v[198:199] op_sel_hi:[1,0,1]
	v_pk_fma_f32 v[18:19], v[18:19], v[172:173], v[200:201] op_sel_hi:[1,0,1]
	v_pk_fma_f32 v[20:21], v[20:21], v[172:173], v[202:203] op_sel_hi:[1,0,1]
	v_exp_f32_e32 v206, v206
	v_exp_f32_e32 v207, v207
	v_exp_f32_e32 v208, v208
	v_exp_f32_e32 v209, v209
	v_exp_f32_e32 v210, v210
	v_exp_f32_e32 v211, v211
	v_exp_f32_e32 v212, v212
	v_exp_f32_e32 v213, v213
	v_pk_add_f32 v[206:207], v[206:207], v[204:205] op_sel:[0,1] op_sel_hi:[1,1]
	v_pk_add_f32 v[208:209], v[208:209], v[204:205] op_sel:[0,1] op_sel_hi:[1,1]
	v_pk_add_f32 v[210:211], v[210:211], v[204:205] op_sel:[0,1] op_sel_hi:[1,1]
	v_pk_add_f32 v[212:213], v[212:213], v[204:205] op_sel:[0,1] op_sel_hi:[1,1]
	v_rcp_f32_e32 v206, v206
	v_rcp_f32_e32 v207, v207
	v_rcp_f32_e32 v208, v208
	v_rcp_f32_e32 v209, v209
	v_rcp_f32_e32 v210, v210
	v_rcp_f32_e32 v211, v211
	v_rcp_f32_e32 v212, v212
	v_rcp_f32_e32 v213, v213
	v_pk_mul_f32 v[30:31], v[30:31], v[206:207]
	v_pk_mul_f32 v[32:33], v[32:33], v[208:209]
	v_pk_mul_f32 v[22:23], v[22:23], v[210:211]
	v_pk_mul_f32 v[24:25], v[24:25], v[212:213]
	v_pk_mul_f32 v[26:27], v[26:27], v[30:31]
	v_pk_mul_f32 v[28:29], v[28:29], v[32:33]
	v_pk_mul_f32 v[18:19], v[18:19], v[22:23]
	v_pk_mul_f32 v[20:21], v[20:21], v[24:25]
	v_cvt_pk_bf16_f32 v30, v26, v27
	v_cvt_pk_bf16_f32 v31, v28, v29
	v_cvt_pk_bf16_f32 v32, v18, v19
	v_cvt_pk_bf16_f32 v33, v20, v21
	global_store_dwordx4 v[214:215], v[30:33], off
	v_lshl_add_u64 v[216:217], v[214:215], 0, s[20:21]
	v_pk_fma_f32 v[14:15], v[14:15], v[170:171], v[188:189] op_sel_hi:[1,0,1]
	v_pk_fma_f32 v[16:17], v[16:17], v[170:171], v[190:191] op_sel_hi:[1,0,1]
	v_pk_fma_f32 v[6:7], v[6:7], v[170:171], v[192:193] op_sel_hi:[1,0,1]
	v_pk_fma_f32 v[8:9], v[8:9], v[170:171], v[194:195] op_sel_hi:[1,0,1]
	v_pk_mul_f32 v[206:207], v[14:15], v[204:205] op_sel_hi:[1,0]
	v_pk_mul_f32 v[208:209], v[16:17], v[204:205] op_sel_hi:[1,0]
	v_pk_mul_f32 v[210:211], v[6:7], v[204:205] op_sel_hi:[1,0]
	v_pk_mul_f32 v[212:213], v[8:9], v[204:205] op_sel_hi:[1,0]
	v_pk_fma_f32 v[10:11], v[10:11], v[170:171], v[196:197] op_sel_hi:[1,0,1]
	v_pk_fma_f32 v[12:13], v[12:13], v[170:171], v[198:199] op_sel_hi:[1,0,1]
	v_pk_fma_f32 v[2:3], v[2:3], v[170:171], v[200:201] op_sel_hi:[1,0,1]
	v_pk_fma_f32 v[4:5], v[4:5], v[170:171], v[202:203] op_sel_hi:[1,0,1]
	v_exp_f32_e32 v206, v206
	v_exp_f32_e32 v207, v207
	v_exp_f32_e32 v208, v208
	v_exp_f32_e32 v209, v209
	v_exp_f32_e32 v210, v210
	v_exp_f32_e32 v211, v211
	v_exp_f32_e32 v212, v212
	v_exp_f32_e32 v213, v213
	v_pk_add_f32 v[206:207], v[206:207], v[204:205] op_sel:[0,1] op_sel_hi:[1,1]
	v_pk_add_f32 v[208:209], v[208:209], v[204:205] op_sel:[0,1] op_sel_hi:[1,1]
	v_pk_add_f32 v[210:211], v[210:211], v[204:205] op_sel:[0,1] op_sel_hi:[1,1]
	v_pk_add_f32 v[212:213], v[212:213], v[204:205] op_sel:[0,1] op_sel_hi:[1,1]
	v_rcp_f32_e32 v206, v206
	v_rcp_f32_e32 v207, v207
	v_rcp_f32_e32 v208, v208
	v_rcp_f32_e32 v209, v209
	v_rcp_f32_e32 v210, v210
	v_rcp_f32_e32 v211, v211
	v_rcp_f32_e32 v212, v212
	v_rcp_f32_e32 v213, v213
	v_pk_mul_f32 v[14:15], v[14:15], v[206:207]
	v_pk_mul_f32 v[16:17], v[16:17], v[208:209]
	v_pk_mul_f32 v[6:7], v[6:7], v[210:211]
	v_pk_mul_f32 v[8:9], v[8:9], v[212:213]
	v_pk_mul_f32 v[10:11], v[10:11], v[14:15]
	v_pk_mul_f32 v[12:13], v[12:13], v[16:17]
	v_pk_mul_f32 v[2:3], v[2:3], v[6:7]
	v_pk_mul_f32 v[4:5], v[4:5], v[8:9]
	v_cvt_pk_bf16_f32 v14, v10, v11
	v_cvt_pk_bf16_f32 v15, v12, v13
	v_cvt_pk_bf16_f32 v16, v2, v3
	v_cvt_pk_bf16_f32 v17, v4, v5
	global_store_dwordx4 v[216:217], v[14:17], off
	s_andn2_b64 vcc, exec, s[4:5]
	s_mov_b64 s[20:21], -1
	s_cbranch_vccnz .LBB0_252
	s_nop 0
	v_mov_b32_e32 v2, s88
	ds_read_b32 v2, v2
	v_mov_b32_e32 v3, s89
	ds_read_b32 v3, v3
	v_mov_b32_e32 v155, v0
	v_mov_b32_e32 v157, v0
	s_waitcnt lgkmcnt(0)
	v_readfirstlane_b32 s3, v2
	s_add_u32 s13, s3, s38
	v_readfirstlane_b32 s0, v3
	s_addc_u32 s15, s0, 0
	s_lshl_b32 s4, s14, 8
	s_ashr_i32 s5, s4, 31
	s_lshl_b64 s[20:21], s[4:5], 2
	s_add_u32 s5, s13, s20
	s_addc_u32 s13, s15, s21
	s_add_u32 s20, s5, s6
	s_addc_u32 s21, s13, s7
	s_add_u32 s3, s3, s40
	s_addc_u32 s0, s0, 0
	s_add_u32 s3, s3, s41
	s_addc_u32 s0, s0, 0
	s_addk_i32 s4, 0xe000
	s_lshr_b32 s4, s4, 12
	s_mulk_i32 s4, 0x1600
	s_addk_i32 s4, 0x1600
	s_cmp_gt_i32 s14, 31
	s_cselect_b32 s46, s4, 0
	s_lshl_b64 s[4:5], s[46:47], 2
	s_add_u32 s3, s3, s4
	s_addc_u32 s0, s0, s5
	s_lshl_b32 s4, s12, 8
	s_ashr_i32 s5, s4, 31
	s_lshl_b64 s[4:5], s[4:5], 2
	s_add_u32 s3, s3, s4
	s_addc_u32 s0, s0, s5
	s_add_u32 s4, s3, s72
	s_addc_u32 s5, s0, 0
	v_lshl_add_u64 v[2:3], s[4:5], 0, v[154:155]
	v_lshl_add_u64 v[2:3], v[2:3], 0, v[156:157]
	v_mov_b32_e32 v159, v0
	v_mov_b32_e32 v161, v0
	v_lshl_add_u64 v[2:3], v[2:3], 0, v[158:159]
	s_mov_b64 s[4:5], 0x10400000
	v_lshl_add_u64 v[4:5], s[20:21], 0, v[160:161]
	v_mov_b32_e32 v163, v0
	v_lshl_add_u64 v[2:3], v[2:3], 0, s[4:5]
	v_lshl_add_u64 v[4:5], v[4:5], 0, v[162:163]
	s_mov_b64 s[4:5], 0x310000
	s_mov_b32 m0, s44
	v_lshl_add_u64 v[6:7], v[4:5], 0, s[4:5]
	s_mov_b64 s[4:5], 0x310200
	global_load_lds_dword v[6:7], off
	v_lshl_add_u64 v[4:5], v[4:5], 0, s[4:5]
	s_mov_b32 m0, s45
	s_andn2_b64 vcc, exec, s[8:9]
	global_load_lds_dword v[4:5], off
	s_mov_b32 m0, s60
	s_nop 0
	global_load_lds_dword v[2:3], off
	s_cbranch_vccnz .LBB0_251
	s_barrier
	s_branch .LBB0_251
